# combo + QK K-fragment LDS reads hoisted (8 reads in flight) in all 7 attention tile bodies
# baseline (speedup 1.0000x reference)
; #define MFMA(a, b, c) __builtin_amdgcn_mfma_f32_32x32x16_bf16((a), (b), (c), 0, 0, 0)
; DI int crow(int r, int hi) { return (r & 3) + 8 * (r >> 2) + 4 * hi; }
; template <class MaskF>
; DI void attn_tile(const int tid, const char* ldsK, const char* ldsV, const bf16x8 (&qr)[4], f32x16 (&o)[2], float& m, float& l, const bool MASKED, MaskF mask) {
;   const int lane = tid & 63, l31 = lane & 31, hi = lane >> 5;
;   f32x16 p0, p1;
; #pragma unroll
;   for (int r = 0; r < 16; ++r) { p0[r] = 0.f; p1[r] = 0.f; }
;   const char* kp = ldsK + l31 * 144 + hi * 16;
; #pragma unroll
;   for (int s = 0; s < 4; ++s) {
;     const bf16x8 k0 = *(const bf16x8*)(kp + s * 32), k1 = *(const bf16x8*)(kp + 32 * 144 + s * 32);
;     p0 = MFMA(k0, qr[s], p0); p1 = MFMA(k1, qr[s], p1);
;   }
;   if (MASKED) {
; #pragma unroll
;     for (int r = 0; r < 16; ++r) {
;       const int kr = crow(r, hi);
;       p0[r] = mask(kr) ? p0[r] : NEGB; p1[r] = mask(kr + 32) ? p1[r] : NEGB;
;     }
; DI void win_item(const Params& p, int it, char* lds) {
;     ...
;   attn_stream(tid, proj, C_KWIN, C_VWIN, khi - klo + 1,
;               [&](int ti, int row) { return b * S_ + (klo + ti) * 64 + row; },
;               [&](int ti) { const int k0 = (klo + ti) * 64; return (k0 + 63 <= q0) && (k0 >= q0 + 31 - 511); },
;               [&](int ti, int kr) { return (unsigned)(t - ((klo + ti) * 64 + kr)) <= 511u; },
;               qr, o, m, lsum, lds);
.LBB0_236:
	ds_read_b128 v[32:35], v160 offset:4608
	ds_read_b128 v[36:39], v160
	ds_read_b128 v[112:115], v160 offset:32
	ds_read_b128 v[116:119], v160 offset:4640
	ds_read_b128 v[120:123], v160 offset:64
	ds_read_b128 v[124:127], v160 offset:4672
	ds_read_b128 v[128:131], v160 offset:96
	ds_read_b128 v[132:135], v160 offset:4704
	s_add_i32 s11, s4, 0xffffff81
	s_sub_i32 s2, s4, 64
	s_waitcnt lgkmcnt(6)
	v_mfma_f32_32x32x16_bf16 v[48:63], v[36:39], v[64:67], 0
	s_cmp_gt_u32 s2, s9
	s_cselect_b64 s[2:3], -1, 0
	s_cmp_lt_i32 s11, s6
	s_cselect_b64 s[12:13], -1, 0
	s_or_b64 s[2:3], s[2:3], s[12:13]
	s_andn2_b64 vcc, exec, s[2:3]
	v_mfma_f32_32x32x16_bf16 v[32:47], v[32:35], v[64:67], 0
	s_waitcnt lgkmcnt(5)
	v_mfma_f32_32x32x16_bf16 v[48:63], v[112:115], v[68:71], v[48:63]
	s_waitcnt lgkmcnt(4)
	v_mfma_f32_32x32x16_bf16 v[32:47], v[116:119], v[68:71], v[32:47]
	s_waitcnt lgkmcnt(3)
	v_mfma_f32_32x32x16_bf16 v[48:63], v[120:123], v[72:75], v[48:63]
	s_waitcnt lgkmcnt(2)
	v_mfma_f32_32x32x16_bf16 v[32:47], v[124:127], v[72:75], v[32:47]
	s_waitcnt lgkmcnt(1)
	v_mfma_f32_32x32x16_bf16 v[48:63], v[128:131], v[76:79], v[48:63]
	s_waitcnt lgkmcnt(0)
	v_mfma_f32_32x32x16_bf16 v[32:47], v[132:135], v[76:79], v[32:47]
	s_cbranch_vccnz .LBB0_238
	v_add_u32_e32 v112, v148, v155
	v_cmp_gt_u32_e32 vcc, s72, v112
	v_subrev_u32_e32 v113, 32, v112
	s_nop 5
	v_cndmask_b32_e32 v48, v194, v48, vcc
	v_cmp_gt_u32_e32 vcc, s72, v113
	v_add_u32_e32 v113, -1, v112
	s_nop 0
	v_cndmask_b32_e32 v32, v194, v32, vcc
	v_cmp_gt_u32_e32 vcc, s72, v113
	v_subrev_u32_e32 v113, 33, v112
	s_nop 0
	v_cndmask_b32_e32 v49, v194, v49, vcc
	v_cmp_gt_u32_e32 vcc, s72, v113
	v_add_u32_e32 v113, -2, v112
	s_nop 0
	v_cndmask_b32_e32 v33, v194, v33, vcc
	v_cmp_gt_u32_e32 vcc, s72, v113
	v_subrev_u32_e32 v113, 34, v112
	s_nop 0
	v_cndmask_b32_e32 v50, v194, v50, vcc
	v_cmp_gt_u32_e32 vcc, s72, v113
	v_add_u32_e32 v113, -3, v112
	s_nop 0
	v_cndmask_b32_e32 v34, v194, v34, vcc
	v_cmp_gt_u32_e32 vcc, s72, v113
	v_subrev_u32_e32 v113, 35, v112
	s_nop 0
	v_cndmask_b32_e32 v51, v194, v51, vcc
	v_cmp_gt_u32_e32 vcc, s72, v113
	v_add_u32_e32 v113, -8, v112
	s_nop 0
	v_cndmask_b32_e32 v35, v194, v35, vcc
	v_cmp_gt_u32_e32 vcc, s72, v113
	v_subrev_u32_e32 v113, 40, v112
	s_nop 0
	v_cndmask_b32_e32 v52, v194, v52, vcc
	v_cmp_gt_u32_e32 vcc, s72, v113
	v_add_u32_e32 v113, -9, v112
	s_nop 0
	v_cndmask_b32_e32 v36, v194, v36, vcc
	v_cmp_gt_u32_e32 vcc, s72, v113
	v_subrev_u32_e32 v113, 41, v112
	s_nop 0
	v_cndmask_b32_e32 v53, v194, v53, vcc
	v_cmp_gt_u32_e32 vcc, s72, v113
	v_add_u32_e32 v113, -10, v112
	s_nop 0
	v_cndmask_b32_e32 v37, v194, v37, vcc
	v_cmp_gt_u32_e32 vcc, s72, v113
	v_subrev_u32_e32 v113, 42, v112
	s_nop 0
	v_cndmask_b32_e32 v54, v194, v54, vcc
	v_cmp_gt_u32_e32 vcc, s72, v113
	v_add_u32_e32 v113, -11, v112
	s_nop 0
	v_cndmask_b32_e32 v38, v194, v38, vcc
	v_cmp_gt_u32_e32 vcc, s72, v113
	v_subrev_u32_e32 v113, 43, v112
	s_nop 0
	v_cndmask_b32_e32 v55, v194, v55, vcc
	v_cmp_gt_u32_e32 vcc, s72, v113
	v_add_u32_e32 v113, -16, v112
	s_nop 0
	v_cndmask_b32_e32 v39, v194, v39, vcc
	v_cmp_gt_u32_e32 vcc, s72, v113
	v_subrev_u32_e32 v113, 48, v112
	s_nop 0
	v_cndmask_b32_e32 v56, v194, v56, vcc
	v_cmp_gt_u32_e32 vcc, s72, v113
	v_subrev_u32_e32 v113, 17, v112
	s_nop 0
	v_cndmask_b32_e32 v40, v194, v40, vcc
	v_cmp_gt_u32_e32 vcc, s72, v113
	v_subrev_u32_e32 v113, 49, v112
	s_nop 0
	v_cndmask_b32_e32 v57, v194, v57, vcc
	v_cmp_gt_u32_e32 vcc, s72, v113
	v_subrev_u32_e32 v113, 18, v112
	s_nop 0
	v_cndmask_b32_e32 v41, v194, v41, vcc
	v_cmp_gt_u32_e32 vcc, s72, v113
	v_subrev_u32_e32 v113, 50, v112
	s_nop 0
	v_cndmask_b32_e32 v58, v194, v58, vcc
	v_cmp_gt_u32_e32 vcc, s72, v113
	v_subrev_u32_e32 v113, 19, v112
	s_nop 0
	v_cndmask_b32_e32 v42, v194, v42, vcc
	v_cmp_gt_u32_e32 vcc, s72, v113
	v_subrev_u32_e32 v113, 51, v112
	s_nop 0
	v_cndmask_b32_e32 v59, v194, v59, vcc
	v_cmp_gt_u32_e32 vcc, s72, v113
	v_subrev_u32_e32 v113, 24, v112
	s_nop 0
	v_cndmask_b32_e32 v43, v194, v43, vcc
	v_cmp_gt_u32_e32 vcc, s72, v113
	v_subrev_u32_e32 v113, 56, v112
	s_nop 0
	v_cndmask_b32_e32 v60, v194, v60, vcc
	v_cmp_gt_u32_e32 vcc, s72, v113
	v_subrev_u32_e32 v113, 25, v112
	s_nop 0
	v_cndmask_b32_e32 v44, v194, v44, vcc
	v_cmp_gt_u32_e32 vcc, s72, v113
	v_subrev_u32_e32 v113, 57, v112
	s_nop 0
	v_cndmask_b32_e32 v61, v194, v61, vcc
	v_cmp_gt_u32_e32 vcc, s72, v113
	v_subrev_u32_e32 v113, 26, v112
	s_nop 0
	v_cndmask_b32_e32 v45, v194, v45, vcc
	v_cmp_gt_u32_e32 vcc, s72, v113
	v_subrev_u32_e32 v113, 58, v112
	s_nop 0
	v_cndmask_b32_e32 v62, v194, v62, vcc
	v_cmp_gt_u32_e32 vcc, s72, v113
	v_subrev_u32_e32 v113, 27, v112
	v_subrev_u32_e32 v112, 59, v112
	v_cndmask_b32_e32 v46, v194, v46, vcc
	v_cmp_gt_u32_e32 vcc, s72, v113
	s_nop 1
	v_cndmask_b32_e32 v63, v194, v63, vcc
	v_cmp_gt_u32_e32 vcc, s72, v112
	s_nop 1
	v_cndmask_b32_e32 v47, v194, v47, vcc

; #define MFMA(a, b, c) __builtin_amdgcn_mfma_f32_32x32x16_bf16((a), (b), (c), 0, 0, 0)
; DI int crow(int r, int hi) { return (r & 3) + 8 * (r >> 2) + 4 * hi; }
; template <class MaskF>
; DI void attn_tile(const int tid, const char* ldsK, const char* ldsV, const bf16x8 (&qr)[4], f32x16 (&o)[2], float& m, float& l, const bool MASKED, MaskF mask) {
;   const int lane = tid & 63, l31 = lane & 31, hi = lane >> 5;
;   f32x16 p0, p1;
; #pragma unroll
;   for (int r = 0; r < 16; ++r) { p0[r] = 0.f; p1[r] = 0.f; }
;   const char* kp = ldsK + l31 * 144 + hi * 16;
; #pragma unroll
;   for (int s = 0; s < 4; ++s) {
;     const bf16x8 k0 = *(const bf16x8*)(kp + s * 32), k1 = *(const bf16x8*)(kp + 32 * 144 + s * 32);
;     p0 = MFMA(k0, qr[s], p0); p1 = MFMA(k1, qr[s], p1);
;   }
;   if (MASKED) {
; #pragma unroll
;     for (int r = 0; r < 16; ++r) {
;       const int kr = crow(r, hi);
;       p0[r] = mask(kr) ? p0[r] : NEGB; p1[r] = mask(kr + 32) ? p1[r] : NEGB;
;     }
; DI void win_item(const Params& p, int it, char* lds) {
;     ...
;   attn_stream(tid, proj, C_KWIN, C_VWIN, khi - klo + 1,
;               [&](int ti, int row) { return b * S_ + (klo + ti) * 64 + row; },
;               [&](int ti) { const int k0 = (klo + ti) * 64; return (k0 + 63 <= q0) && (k0 >= q0 + 31 - 511); },
;               [&](int ti, int kr) { return (unsigned)(t - ((klo + ti) * 64 + kr)) <= 511u; },
;               qr, o, m, lsum, lds);
.LBB0_243:
	ds_read_b128 v[32:35], v160 offset:23040
	ds_read_b128 v[36:39], v160 offset:18432
	ds_read_b128 v[112:115], v160 offset:18464
	ds_read_b128 v[116:119], v160 offset:23072
	ds_read_b128 v[120:123], v160 offset:18496
	ds_read_b128 v[124:127], v160 offset:23104
	ds_read_b128 v[128:131], v160 offset:18528
	ds_read_b128 v[132:135], v160 offset:23136
	s_sub_i32 s11, s4, 63
	s_cmp_gt_u32 s4, s9
	s_waitcnt lgkmcnt(6)
	v_mfma_f32_32x32x16_bf16 v[48:63], v[36:39], v[64:67], 0
	s_cselect_b64 s[2:3], -1, 0
	s_cmp_lt_i32 s11, s6
	s_cselect_b64 s[12:13], -1, 0
	s_or_b64 s[2:3], s[2:3], s[12:13]
	s_andn2_b64 vcc, exec, s[2:3]
	v_mfma_f32_32x32x16_bf16 v[32:47], v[32:35], v[64:67], 0
	s_waitcnt lgkmcnt(5)
	v_mfma_f32_32x32x16_bf16 v[48:63], v[112:115], v[68:71], v[48:63]
	s_waitcnt lgkmcnt(4)
	v_mfma_f32_32x32x16_bf16 v[32:47], v[116:119], v[68:71], v[32:47]
	s_waitcnt lgkmcnt(3)
	v_mfma_f32_32x32x16_bf16 v[48:63], v[120:123], v[72:75], v[48:63]
	s_waitcnt lgkmcnt(2)
	v_mfma_f32_32x32x16_bf16 v[32:47], v[124:127], v[72:75], v[32:47]
	s_waitcnt lgkmcnt(1)
	v_mfma_f32_32x32x16_bf16 v[48:63], v[128:131], v[76:79], v[48:63]
	s_waitcnt lgkmcnt(0)
	v_mfma_f32_32x32x16_bf16 v[32:47], v[132:135], v[76:79], v[32:47]
	s_cbranch_vccnz .LBB0_245
	v_add_u32_e32 v112, v148, v154
	v_subrev_u32_e32 v113, 64, v112
	v_cmp_gt_u32_e32 vcc, s72, v113
	v_add_u32_e32 v113, 0xffffffa0, v112
	s_nop 4
	v_cndmask_b32_e32 v48, v194, v48, vcc
	v_cmp_gt_u32_e32 vcc, s72, v113
	v_add_u32_e32 v113, 0xffffffbf, v112
	s_nop 0
	v_cndmask_b32_e32 v32, v194, v32, vcc
	v_cmp_gt_u32_e32 vcc, s72, v113
	v_add_u32_e32 v113, 0xffffff9f, v112
	s_nop 0
	v_cndmask_b32_e32 v49, v194, v49, vcc
	v_cmp_gt_u32_e32 vcc, s72, v113
	v_add_u32_e32 v113, 0xffffffbe, v112
	s_nop 0
	v_cndmask_b32_e32 v33, v194, v33, vcc
	v_cmp_gt_u32_e32 vcc, s72, v113
	v_add_u32_e32 v113, 0xffffff9e, v112
	s_nop 0
	v_cndmask_b32_e32 v50, v194, v50, vcc
	v_cmp_gt_u32_e32 vcc, s72, v113
	v_add_u32_e32 v113, 0xffffffbd, v112
	s_nop 0
	v_cndmask_b32_e32 v34, v194, v34, vcc
	v_cmp_gt_u32_e32 vcc, s72, v113
	v_add_u32_e32 v113, 0xffffff9d, v112
	s_nop 0
	v_cndmask_b32_e32 v51, v194, v51, vcc
	v_cmp_gt_u32_e32 vcc, s72, v113
	v_add_u32_e32 v113, 0xffffffb8, v112
	s_nop 0
	v_cndmask_b32_e32 v35, v194, v35, vcc
	v_cmp_gt_u32_e32 vcc, s72, v113
	v_add_u32_e32 v113, 0xffffff98, v112
	s_nop 0
	v_cndmask_b32_e32 v52, v194, v52, vcc
	v_cmp_gt_u32_e32 vcc, s72, v113
	v_add_u32_e32 v113, 0xffffffb7, v112
	s_nop 0
	v_cndmask_b32_e32 v36, v194, v36, vcc
	v_cmp_gt_u32_e32 vcc, s72, v113
	v_add_u32_e32 v113, 0xffffff97, v112
	s_nop 0
	v_cndmask_b32_e32 v53, v194, v53, vcc
	v_cmp_gt_u32_e32 vcc, s72, v113
	v_add_u32_e32 v113, 0xffffffb6, v112
	s_nop 0
	v_cndmask_b32_e32 v37, v194, v37, vcc
	v_cmp_gt_u32_e32 vcc, s72, v113
	v_add_u32_e32 v113, 0xffffff96, v112
	s_nop 0
	v_cndmask_b32_e32 v54, v194, v54, vcc
	v_cmp_gt_u32_e32 vcc, s72, v113
	v_add_u32_e32 v113, 0xffffffb5, v112
	s_nop 0
	v_cndmask_b32_e32 v38, v194, v38, vcc
	v_cmp_gt_u32_e32 vcc, s72, v113
	v_add_u32_e32 v113, 0xffffff95, v112
	s_nop 0
	v_cndmask_b32_e32 v55, v194, v55, vcc
	v_cmp_gt_u32_e32 vcc, s72, v113
	v_add_u32_e32 v113, 0xffffffb0, v112
	s_nop 0
	v_cndmask_b32_e32 v39, v194, v39, vcc
	v_cmp_gt_u32_e32 vcc, s72, v113
	v_add_u32_e32 v113, 0xffffff90, v112
	s_nop 0
	v_cndmask_b32_e32 v56, v194, v56, vcc
	v_cmp_gt_u32_e32 vcc, s72, v113
	v_add_u32_e32 v113, 0xffffffaf, v112
	s_nop 0
	v_cndmask_b32_e32 v40, v194, v40, vcc
	v_cmp_gt_u32_e32 vcc, s72, v113
	v_add_u32_e32 v113, 0xffffff8f, v112
	s_nop 0
	v_cndmask_b32_e32 v57, v194, v57, vcc
	v_cmp_gt_u32_e32 vcc, s72, v113
	v_add_u32_e32 v113, 0xffffffae, v112
	s_nop 0
	v_cndmask_b32_e32 v41, v194, v41, vcc
	v_cmp_gt_u32_e32 vcc, s72, v113
	v_add_u32_e32 v113, 0xffffff8e, v112
	s_nop 0
	v_cndmask_b32_e32 v58, v194, v58, vcc
	v_cmp_gt_u32_e32 vcc, s72, v113
	v_add_u32_e32 v113, 0xffffffad, v112
	s_nop 0
	v_cndmask_b32_e32 v42, v194, v42, vcc
	v_cmp_gt_u32_e32 vcc, s72, v113
	v_add_u32_e32 v113, 0xffffff8d, v112
	s_nop 0
	v_cndmask_b32_e32 v59, v194, v59, vcc
	v_cmp_gt_u32_e32 vcc, s72, v113
	v_add_u32_e32 v113, 0xffffffa8, v112
	s_nop 0
	v_cndmask_b32_e32 v43, v194, v43, vcc
	v_cmp_gt_u32_e32 vcc, s72, v113
	v_add_u32_e32 v113, 0xffffff88, v112
	s_nop 0
	v_cndmask_b32_e32 v60, v194, v60, vcc
	v_cmp_gt_u32_e32 vcc, s72, v113
	v_add_u32_e32 v113, 0xffffffa7, v112
	s_nop 0
	v_cndmask_b32_e32 v44, v194, v44, vcc
	v_cmp_gt_u32_e32 vcc, s72, v113
	v_add_u32_e32 v113, 0xffffff87, v112
	s_nop 0
	v_cndmask_b32_e32 v61, v194, v61, vcc
	v_cmp_gt_u32_e32 vcc, s72, v113
	v_add_u32_e32 v113, 0xffffffa6, v112
	s_nop 0
	v_cndmask_b32_e32 v45, v194, v45, vcc
	v_cmp_gt_u32_e32 vcc, s72, v113
	v_add_u32_e32 v113, 0xffffff86, v112
	s_nop 0
	v_cndmask_b32_e32 v62, v194, v62, vcc
	v_cmp_gt_u32_e32 vcc, s72, v113
	v_add_u32_e32 v113, 0xffffffa5, v112
	v_add_u32_e32 v112, 0xffffff85, v112
	v_cndmask_b32_e32 v46, v194, v46, vcc
	v_cmp_gt_u32_e32 vcc, s72, v113
	s_nop 1
	v_cndmask_b32_e32 v63, v194, v63, vcc
	v_cmp_gt_u32_e32 vcc, s72, v112
	s_nop 1
	v_cndmask_b32_e32 v47, v194, v47, vcc

; #define MFMA(a, b, c) __builtin_amdgcn_mfma_f32_32x32x16_bf16((a), (b), (c), 0, 0, 0)
; DI int crow(int r, int hi) { return (r & 3) + 8 * (r >> 2) + 4 * hi; }
; template <class MaskF>
; DI void attn_tile(const int tid, const char* ldsK, const char* ldsV, const bf16x8 (&qr)[4], f32x16 (&o)[2], float& m, float& l, const bool MASKED, MaskF mask) {
;   const int lane = tid & 63, l31 = lane & 31, hi = lane >> 5;
;   f32x16 p0, p1;
; #pragma unroll
;   for (int r = 0; r < 16; ++r) { p0[r] = 0.f; p1[r] = 0.f; }
;   const char* kp = ldsK + l31 * 144 + hi * 16;
; #pragma unroll
;   for (int s = 0; s < 4; ++s) {
;     const bf16x8 k0 = *(const bf16x8*)(kp + s * 32), k1 = *(const bf16x8*)(kp + 32 * 144 + s * 32);
;     p0 = MFMA(k0, qr[s], p0); p1 = MFMA(k1, qr[s], p1);
;   }
;   if (MASKED) {
; #pragma unroll
;     for (int r = 0; r < 16; ++r) {
;       const int kr = crow(r, hi);
;       p0[r] = mask(kr) ? p0[r] : NEGB; p1[r] = mask(kr + 32) ? p1[r] : NEGB;
;     }
; DI void win_item(const Params& p, int it, char* lds) {
;     ...
;   attn_stream(tid, proj, C_KWIN, C_VWIN, khi - klo + 1,
;               [&](int ti, int row) { return b * S_ + (klo + ti) * 64 + row; },
;               [&](int ti) { const int k0 = (klo + ti) * 64; return (k0 + 63 <= q0) && (k0 >= q0 + 31 - 511); },
;               [&](int ti, int kr) { return (unsigned)(t - ((klo + ti) * 64 + kr)) <= 511u; },
;               qr, o, m, lsum, lds);
.LBB0_255:
	ds_read_b128 v[32:35], v161 offset:4608
	ds_read_b128 v[36:39], v161
	ds_read_b128 v[112:115], v161 offset:32
	ds_read_b128 v[116:119], v161 offset:4640
	ds_read_b128 v[120:123], v161 offset:64
	ds_read_b128 v[124:127], v161 offset:4672
	ds_read_b128 v[128:131], v161 offset:96
	ds_read_b128 v[132:135], v161 offset:4704
	s_add_i32 s11, s4, 0xffffff81
	s_sub_i32 s2, s4, 64
	s_waitcnt lgkmcnt(6)
	v_mfma_f32_32x32x16_bf16 v[48:63], v[36:39], v[64:67], 0
	s_cmp_gt_u32 s2, s5
	s_cselect_b64 s[2:3], -1, 0
	s_cmp_lt_i32 s11, s9
	s_cselect_b64 s[12:13], -1, 0
	s_or_b64 s[2:3], s[2:3], s[12:13]
	s_andn2_b64 vcc, exec, s[2:3]
	v_mfma_f32_32x32x16_bf16 v[32:47], v[32:35], v[64:67], 0
	s_waitcnt lgkmcnt(5)
	v_mfma_f32_32x32x16_bf16 v[48:63], v[112:115], v[68:71], v[48:63]
	s_waitcnt lgkmcnt(4)
	v_mfma_f32_32x32x16_bf16 v[32:47], v[116:119], v[68:71], v[32:47]
	s_waitcnt lgkmcnt(3)
	v_mfma_f32_32x32x16_bf16 v[48:63], v[120:123], v[72:75], v[48:63]
	s_waitcnt lgkmcnt(2)
	v_mfma_f32_32x32x16_bf16 v[32:47], v[124:127], v[72:75], v[32:47]
	s_waitcnt lgkmcnt(1)
	v_mfma_f32_32x32x16_bf16 v[48:63], v[128:131], v[76:79], v[48:63]
	s_waitcnt lgkmcnt(0)
	v_mfma_f32_32x32x16_bf16 v[32:47], v[132:135], v[76:79], v[32:47]
	s_cbranch_vccnz .LBB0_257
	v_add_u32_e32 v112, v150, v156
	v_cmp_gt_u32_e32 vcc, s72, v112
	v_subrev_u32_e32 v113, 32, v112
	s_nop 5
	v_cndmask_b32_e32 v48, v194, v48, vcc
	v_cmp_gt_u32_e32 vcc, s72, v113
	v_add_u32_e32 v113, -1, v112
	s_nop 0
	v_cndmask_b32_e32 v32, v194, v32, vcc
	v_cmp_gt_u32_e32 vcc, s72, v113
	v_subrev_u32_e32 v113, 33, v112
	s_nop 0
	v_cndmask_b32_e32 v49, v194, v49, vcc
	v_cmp_gt_u32_e32 vcc, s72, v113
	v_add_u32_e32 v113, -2, v112
	s_nop 0
	v_cndmask_b32_e32 v33, v194, v33, vcc
	v_cmp_gt_u32_e32 vcc, s72, v113
	v_subrev_u32_e32 v113, 34, v112
	s_nop 0
	v_cndmask_b32_e32 v50, v194, v50, vcc
	v_cmp_gt_u32_e32 vcc, s72, v113
	v_add_u32_e32 v113, -3, v112
	s_nop 0
	v_cndmask_b32_e32 v34, v194, v34, vcc
	v_cmp_gt_u32_e32 vcc, s72, v113
	v_subrev_u32_e32 v113, 35, v112
	s_nop 0
	v_cndmask_b32_e32 v51, v194, v51, vcc
	v_cmp_gt_u32_e32 vcc, s72, v113
	v_add_u32_e32 v113, -8, v112
	s_nop 0
	v_cndmask_b32_e32 v35, v194, v35, vcc
	v_cmp_gt_u32_e32 vcc, s72, v113
	v_subrev_u32_e32 v113, 40, v112
	s_nop 0
	v_cndmask_b32_e32 v52, v194, v52, vcc
	v_cmp_gt_u32_e32 vcc, s72, v113
	v_add_u32_e32 v113, -9, v112
	s_nop 0
	v_cndmask_b32_e32 v36, v194, v36, vcc
	v_cmp_gt_u32_e32 vcc, s72, v113
	v_subrev_u32_e32 v113, 41, v112
	s_nop 0
	v_cndmask_b32_e32 v53, v194, v53, vcc
	v_cmp_gt_u32_e32 vcc, s72, v113
	v_add_u32_e32 v113, -10, v112
	s_nop 0
	v_cndmask_b32_e32 v37, v194, v37, vcc
	v_cmp_gt_u32_e32 vcc, s72, v113
	v_subrev_u32_e32 v113, 42, v112
	s_nop 0
	v_cndmask_b32_e32 v54, v194, v54, vcc
	v_cmp_gt_u32_e32 vcc, s72, v113
	v_add_u32_e32 v113, -11, v112
	s_nop 0
	v_cndmask_b32_e32 v38, v194, v38, vcc
	v_cmp_gt_u32_e32 vcc, s72, v113
	v_subrev_u32_e32 v113, 43, v112
	s_nop 0
	v_cndmask_b32_e32 v55, v194, v55, vcc
	v_cmp_gt_u32_e32 vcc, s72, v113
	v_add_u32_e32 v113, -16, v112
	s_nop 0
	v_cndmask_b32_e32 v39, v194, v39, vcc
	v_cmp_gt_u32_e32 vcc, s72, v113
	v_subrev_u32_e32 v113, 48, v112
	s_nop 0
	v_cndmask_b32_e32 v56, v194, v56, vcc
	v_cmp_gt_u32_e32 vcc, s72, v113
	v_subrev_u32_e32 v113, 17, v112
	s_nop 0
	v_cndmask_b32_e32 v40, v194, v40, vcc
	v_cmp_gt_u32_e32 vcc, s72, v113
	v_subrev_u32_e32 v113, 49, v112
	s_nop 0
	v_cndmask_b32_e32 v57, v194, v57, vcc
	v_cmp_gt_u32_e32 vcc, s72, v113
	v_subrev_u32_e32 v113, 18, v112
	s_nop 0
	v_cndmask_b32_e32 v41, v194, v41, vcc
	v_cmp_gt_u32_e32 vcc, s72, v113
	v_subrev_u32_e32 v113, 50, v112
	s_nop 0
	v_cndmask_b32_e32 v58, v194, v58, vcc
	v_cmp_gt_u32_e32 vcc, s72, v113
	v_subrev_u32_e32 v113, 19, v112
	s_nop 0
	v_cndmask_b32_e32 v42, v194, v42, vcc
	v_cmp_gt_u32_e32 vcc, s72, v113
	v_subrev_u32_e32 v113, 51, v112
	s_nop 0
	v_cndmask_b32_e32 v59, v194, v59, vcc
	v_cmp_gt_u32_e32 vcc, s72, v113
	v_subrev_u32_e32 v113, 24, v112
	s_nop 0
	v_cndmask_b32_e32 v43, v194, v43, vcc
	v_cmp_gt_u32_e32 vcc, s72, v113
	v_subrev_u32_e32 v113, 56, v112
	s_nop 0
	v_cndmask_b32_e32 v60, v194, v60, vcc
	v_cmp_gt_u32_e32 vcc, s72, v113
	v_subrev_u32_e32 v113, 25, v112
	s_nop 0
	v_cndmask_b32_e32 v44, v194, v44, vcc
	v_cmp_gt_u32_e32 vcc, s72, v113
	v_subrev_u32_e32 v113, 57, v112
	s_nop 0
	v_cndmask_b32_e32 v61, v194, v61, vcc
	v_cmp_gt_u32_e32 vcc, s72, v113
	v_subrev_u32_e32 v113, 26, v112
	s_nop 0
	v_cndmask_b32_e32 v45, v194, v45, vcc
	v_cmp_gt_u32_e32 vcc, s72, v113
	v_subrev_u32_e32 v113, 58, v112
	s_nop 0
	v_cndmask_b32_e32 v62, v194, v62, vcc
	v_cmp_gt_u32_e32 vcc, s72, v113
	v_subrev_u32_e32 v113, 27, v112
	v_subrev_u32_e32 v112, 59, v112
	v_cndmask_b32_e32 v46, v194, v46, vcc
	v_cmp_gt_u32_e32 vcc, s72, v113
	s_nop 1
	v_cndmask_b32_e32 v63, v194, v63, vcc
	v_cmp_gt_u32_e32 vcc, s72, v112
	s_nop 1
	v_cndmask_b32_e32 v47, v194, v47, vcc

; #define MFMA(a, b, c) __builtin_amdgcn_mfma_f32_32x32x16_bf16((a), (b), (c), 0, 0, 0)
; DI int crow(int r, int hi) { return (r & 3) + 8 * (r >> 2) + 4 * hi; }
; template <class MaskF>
; DI void attn_tile(const int tid, const char* ldsK, const char* ldsV, const bf16x8 (&qr)[4], f32x16 (&o)[2], float& m, float& l, const bool MASKED, MaskF mask) {
;   const int lane = tid & 63, l31 = lane & 31, hi = lane >> 5;
;   f32x16 p0, p1;
; #pragma unroll
;   for (int r = 0; r < 16; ++r) { p0[r] = 0.f; p1[r] = 0.f; }
;   const char* kp = ldsK + l31 * 144 + hi * 16;
; #pragma unroll
;   for (int s = 0; s < 4; ++s) {
;     const bf16x8 k0 = *(const bf16x8*)(kp + s * 32), k1 = *(const bf16x8*)(kp + 32 * 144 + s * 32);
;     p0 = MFMA(k0, qr[s], p0); p1 = MFMA(k1, qr[s], p1);
;   }
;   if (MASKED) {
; #pragma unroll
;     for (int r = 0; r < 16; ++r) {
;       const int kr = crow(r, hi);
;       p0[r] = mask(kr) ? p0[r] : NEGB; p1[r] = mask(kr + 32) ? p1[r] : NEGB;
;     }
; DI void win_item(const Params& p, int it, char* lds) {
;     ...
;   attn_stream(tid, proj, C_KWIN, C_VWIN, khi - klo + 1,
;               [&](int ti, int row) { return b * S_ + (klo + ti) * 64 + row; },
;               [&](int ti) { const int k0 = (klo + ti) * 64; return (k0 + 63 <= q0) && (k0 >= q0 + 31 - 511); },
;               [&](int ti, int kr) { return (unsigned)(t - ((klo + ti) * 64 + kr)) <= 511u; },
;               qr, o, m, lsum, lds);
.LBB0_262:
	ds_read_b128 v[32:35], v161 offset:23040
	ds_read_b128 v[36:39], v161 offset:18432
	ds_read_b128 v[112:115], v161 offset:18464
	ds_read_b128 v[116:119], v161 offset:23072
	ds_read_b128 v[120:123], v161 offset:18496
	ds_read_b128 v[124:127], v161 offset:23104
	ds_read_b128 v[128:131], v161 offset:18528
	ds_read_b128 v[132:135], v161 offset:23136
	s_sub_i32 s11, s4, 63
	s_cmp_gt_u32 s4, s5
	s_waitcnt lgkmcnt(6)
	v_mfma_f32_32x32x16_bf16 v[48:63], v[36:39], v[64:67], 0
	s_cselect_b64 s[2:3], -1, 0
	s_cmp_lt_i32 s11, s9
	s_cselect_b64 s[12:13], -1, 0
	s_or_b64 s[2:3], s[2:3], s[12:13]
	s_andn2_b64 vcc, exec, s[2:3]
	v_mfma_f32_32x32x16_bf16 v[32:47], v[32:35], v[64:67], 0
	s_waitcnt lgkmcnt(5)
	v_mfma_f32_32x32x16_bf16 v[48:63], v[112:115], v[68:71], v[48:63]
	s_waitcnt lgkmcnt(4)
	v_mfma_f32_32x32x16_bf16 v[32:47], v[116:119], v[68:71], v[32:47]
	s_waitcnt lgkmcnt(3)
	v_mfma_f32_32x32x16_bf16 v[48:63], v[120:123], v[72:75], v[48:63]
	s_waitcnt lgkmcnt(2)
	v_mfma_f32_32x32x16_bf16 v[32:47], v[124:127], v[72:75], v[32:47]
	s_waitcnt lgkmcnt(1)
	v_mfma_f32_32x32x16_bf16 v[48:63], v[128:131], v[76:79], v[48:63]
	s_waitcnt lgkmcnt(0)
	v_mfma_f32_32x32x16_bf16 v[32:47], v[132:135], v[76:79], v[32:47]
	s_cbranch_vccnz .LBB0_264
	v_add_u32_e32 v112, v150, v155
	v_subrev_u32_e32 v113, 64, v112
	v_cmp_gt_u32_e32 vcc, s72, v113
	v_add_u32_e32 v113, 0xffffffa0, v112
	s_nop 4
	v_cndmask_b32_e32 v48, v194, v48, vcc
	v_cmp_gt_u32_e32 vcc, s72, v113
	v_add_u32_e32 v113, 0xffffffbf, v112
	s_nop 0
	v_cndmask_b32_e32 v32, v194, v32, vcc
	v_cmp_gt_u32_e32 vcc, s72, v113
	v_add_u32_e32 v113, 0xffffff9f, v112
	s_nop 0
	v_cndmask_b32_e32 v49, v194, v49, vcc
	v_cmp_gt_u32_e32 vcc, s72, v113
	v_add_u32_e32 v113, 0xffffffbe, v112
	s_nop 0
	v_cndmask_b32_e32 v33, v194, v33, vcc
	v_cmp_gt_u32_e32 vcc, s72, v113
	v_add_u32_e32 v113, 0xffffff9e, v112
	s_nop 0
	v_cndmask_b32_e32 v50, v194, v50, vcc
	v_cmp_gt_u32_e32 vcc, s72, v113
	v_add_u32_e32 v113, 0xffffffbd, v112
	s_nop 0
	v_cndmask_b32_e32 v34, v194, v34, vcc
	v_cmp_gt_u32_e32 vcc, s72, v113
	v_add_u32_e32 v113, 0xffffff9d, v112
	s_nop 0
	v_cndmask_b32_e32 v51, v194, v51, vcc
	v_cmp_gt_u32_e32 vcc, s72, v113
	v_add_u32_e32 v113, 0xffffffb8, v112
	s_nop 0
	v_cndmask_b32_e32 v35, v194, v35, vcc
	v_cmp_gt_u32_e32 vcc, s72, v113
	v_add_u32_e32 v113, 0xffffff98, v112
	s_nop 0
	v_cndmask_b32_e32 v52, v194, v52, vcc
	v_cmp_gt_u32_e32 vcc, s72, v113
	v_add_u32_e32 v113, 0xffffffb7, v112
	s_nop 0
	v_cndmask_b32_e32 v36, v194, v36, vcc
	v_cmp_gt_u32_e32 vcc, s72, v113
	v_add_u32_e32 v113, 0xffffff97, v112
	s_nop 0
	v_cndmask_b32_e32 v53, v194, v53, vcc
	v_cmp_gt_u32_e32 vcc, s72, v113
	v_add_u32_e32 v113, 0xffffffb6, v112
	s_nop 0
	v_cndmask_b32_e32 v37, v194, v37, vcc
	v_cmp_gt_u32_e32 vcc, s72, v113
	v_add_u32_e32 v113, 0xffffff96, v112
	s_nop 0
	v_cndmask_b32_e32 v54, v194, v54, vcc
	v_cmp_gt_u32_e32 vcc, s72, v113
	v_add_u32_e32 v113, 0xffffffb5, v112
	s_nop 0
	v_cndmask_b32_e32 v38, v194, v38, vcc
	v_cmp_gt_u32_e32 vcc, s72, v113
	v_add_u32_e32 v113, 0xffffff95, v112
	s_nop 0
	v_cndmask_b32_e32 v55, v194, v55, vcc
	v_cmp_gt_u32_e32 vcc, s72, v113
	v_add_u32_e32 v113, 0xffffffb0, v112
	s_nop 0
	v_cndmask_b32_e32 v39, v194, v39, vcc
	v_cmp_gt_u32_e32 vcc, s72, v113
	v_add_u32_e32 v113, 0xffffff90, v112
	s_nop 0
	v_cndmask_b32_e32 v56, v194, v56, vcc
	v_cmp_gt_u32_e32 vcc, s72, v113
	v_add_u32_e32 v113, 0xffffffaf, v112
	s_nop 0
	v_cndmask_b32_e32 v40, v194, v40, vcc
	v_cmp_gt_u32_e32 vcc, s72, v113
	v_add_u32_e32 v113, 0xffffff8f, v112
	s_nop 0
	v_cndmask_b32_e32 v57, v194, v57, vcc
	v_cmp_gt_u32_e32 vcc, s72, v113
	v_add_u32_e32 v113, 0xffffffae, v112
	s_nop 0
	v_cndmask_b32_e32 v41, v194, v41, vcc
	v_cmp_gt_u32_e32 vcc, s72, v113
	v_add_u32_e32 v113, 0xffffff8e, v112
	s_nop 0
	v_cndmask_b32_e32 v58, v194, v58, vcc
	v_cmp_gt_u32_e32 vcc, s72, v113
	v_add_u32_e32 v113, 0xffffffad, v112
	s_nop 0
	v_cndmask_b32_e32 v42, v194, v42, vcc
	v_cmp_gt_u32_e32 vcc, s72, v113
	v_add_u32_e32 v113, 0xffffff8d, v112
	s_nop 0
	v_cndmask_b32_e32 v59, v194, v59, vcc
	v_cmp_gt_u32_e32 vcc, s72, v113
	v_add_u32_e32 v113, 0xffffffa8, v112
	s_nop 0
	v_cndmask_b32_e32 v43, v194, v43, vcc
	v_cmp_gt_u32_e32 vcc, s72, v113
	v_add_u32_e32 v113, 0xffffff88, v112
	s_nop 0
	v_cndmask_b32_e32 v60, v194, v60, vcc
	v_cmp_gt_u32_e32 vcc, s72, v113
	v_add_u32_e32 v113, 0xffffffa7, v112
	s_nop 0
	v_cndmask_b32_e32 v44, v194, v44, vcc
	v_cmp_gt_u32_e32 vcc, s72, v113
	v_add_u32_e32 v113, 0xffffff87, v112
	s_nop 0
	v_cndmask_b32_e32 v61, v194, v61, vcc
	v_cmp_gt_u32_e32 vcc, s72, v113
	v_add_u32_e32 v113, 0xffffffa6, v112
	s_nop 0
	v_cndmask_b32_e32 v45, v194, v45, vcc
	v_cmp_gt_u32_e32 vcc, s72, v113
	v_add_u32_e32 v113, 0xffffff86, v112
	s_nop 0
	v_cndmask_b32_e32 v62, v194, v62, vcc
	v_cmp_gt_u32_e32 vcc, s72, v113
	v_add_u32_e32 v113, 0xffffffa5, v112
	v_add_u32_e32 v112, 0xffffff85, v112
	v_cndmask_b32_e32 v46, v194, v46, vcc
	v_cmp_gt_u32_e32 vcc, s72, v113
	s_nop 1
	v_cndmask_b32_e32 v63, v194, v63, vcc
	v_cmp_gt_u32_e32 vcc, s72, v112
	s_nop 1
	v_cndmask_b32_e32 v47, v194, v47, vcc

; #define MFMA(a, b, c) __builtin_amdgcn_mfma_f32_32x32x16_bf16((a), (b), (c), 0, 0, 0)
; DI int crow(int r, int hi) { return (r & 3) + 8 * (r >> 2) + 4 * hi; }
; template <class MaskF>
; DI void attn_tile(const int tid, const char* ldsK, const char* ldsV, const bf16x8 (&qr)[4], f32x16 (&o)[2], float& m, float& l, const bool MASKED, MaskF mask) {
;   const int lane = tid & 63, l31 = lane & 31, hi = lane >> 5;
;   f32x16 p0, p1;
; #pragma unroll
;   for (int r = 0; r < 16; ++r) { p0[r] = 0.f; p1[r] = 0.f; }
;   const char* kp = ldsK + l31 * 144 + hi * 16;
; #pragma unroll
;   for (int s = 0; s < 4; ++s) {
;     const bf16x8 k0 = *(const bf16x8*)(kp + s * 32), k1 = *(const bf16x8*)(kp + 32 * 144 + s * 32);
;     p0 = MFMA(k0, qr[s], p0); p1 = MFMA(k1, qr[s], p1);
;   }
;   if (MASKED) {
; #pragma unroll
;     for (int r = 0; r < 16; ++r) {
;       const int kr = crow(r, hi);
;       p0[r] = mask(kr) ? p0[r] : NEGB; p1[r] = mask(kr + 32) ? p1[r] : NEGB;
;     }
; DI void dil_item(const Params& p, int it, char* lds) {
;     ...
;   for (int tt = tt0; tt < 4; ++tt) {
;     const int tk0 = m0 - 128 + 64 * tt;
;     if (tk0 + 63 >= wlo && tk0 <= whi) {
;       attn_tile(tid, lds + tt * 18432, lds + tt * 18432 + 9216, qr, o, m, lsum, !(tk0 + 63 <= wlo + 128 && tk0 >= whi - 128), [&](int kr) { return (unsigned)(mq - (tk0 + kr)) <= 128u; });
;     }
.LBB0_277:
	s_add_i32 s13, s12, 63
	s_cmp_lt_i32 s13, s1
	s_cselect_b64 s[14:15], -1, 0
	s_cmp_gt_i32 s12, s3
	s_cselect_b64 s[16:17], -1, 0
	s_or_b64 s[14:15], s[14:15], s[16:17]
	s_and_b64 vcc, exec, s[14:15]
	s_cbranch_vccnz .LBB0_276
	v_add_u32_e32 v88, s7, v118
	ds_read_b128 v[32:35], v88 offset:4608
	ds_read_b128 v[36:39], v88
	ds_read_b128 v[80:83], v88 offset:32
	ds_read_b128 v[84:87], v88 offset:4640
	ds_read_b128 v[124:127], v88 offset:64
	ds_read_b128 v[128:131], v88 offset:4672
	ds_read_b128 v[132:135], v88 offset:96
	ds_read_b128 v[136:139], v88 offset:4704
	s_cmp_gt_i32 s13, s0
	s_cselect_b64 s[14:15], -1, 0
	s_waitcnt lgkmcnt(6)
	v_mfma_f32_32x32x16_bf16 v[48:63], v[36:39], v[64:67], 0
	s_cmp_lt_i32 s12, s5
	s_cselect_b64 s[16:17], -1, 0
	s_or_b64 s[14:15], s[14:15], s[16:17]
	s_andn2_b64 vcc, exec, s[14:15]
	v_mfma_f32_32x32x16_bf16 v[32:47], v[32:35], v[64:67], 0
	s_waitcnt lgkmcnt(5)
	v_mfma_f32_32x32x16_bf16 v[48:63], v[80:83], v[68:71], v[48:63]
	s_waitcnt lgkmcnt(4)
	v_mfma_f32_32x32x16_bf16 v[32:47], v[84:87], v[68:71], v[32:47]
	s_waitcnt lgkmcnt(3)
	v_mfma_f32_32x32x16_bf16 v[48:63], v[124:127], v[72:75], v[48:63]
	s_waitcnt lgkmcnt(2)
	v_mfma_f32_32x32x16_bf16 v[32:47], v[128:131], v[72:75], v[32:47]
	s_waitcnt lgkmcnt(1)
	v_mfma_f32_32x32x16_bf16 v[48:63], v[132:135], v[76:79], v[48:63]
	s_waitcnt lgkmcnt(0)
	v_mfma_f32_32x32x16_bf16 v[32:47], v[136:139], v[76:79], v[32:47]
	s_cbranch_vccnz .LBB0_280
	v_cmp_gt_u32_e32 vcc, s85, v120
	v_subrev_u32_e32 v80, 32, v120
	s_nop 6
	v_cndmask_b32_e32 v48, v194, v48, vcc
	v_cmp_gt_u32_e32 vcc, s85, v80
	v_add_u32_e32 v80, -1, v120
	s_nop 0
	v_cndmask_b32_e32 v32, v194, v32, vcc
	v_cmp_gt_u32_e32 vcc, s85, v80
	v_subrev_u32_e32 v80, 33, v120
	s_nop 0
	v_cndmask_b32_e32 v49, v194, v49, vcc
	v_cmp_gt_u32_e32 vcc, s85, v80
	v_add_u32_e32 v80, -2, v120
	s_nop 0
	v_cndmask_b32_e32 v33, v194, v33, vcc
	v_cmp_gt_u32_e32 vcc, s85, v80
	v_subrev_u32_e32 v80, 34, v120
	s_nop 0
	v_cndmask_b32_e32 v50, v194, v50, vcc
	v_cmp_gt_u32_e32 vcc, s85, v80
	v_add_u32_e32 v80, -3, v120
	s_nop 0
	v_cndmask_b32_e32 v34, v194, v34, vcc
	v_cmp_gt_u32_e32 vcc, s85, v80
	v_subrev_u32_e32 v80, 35, v120
	s_nop 0
	v_cndmask_b32_e32 v51, v194, v51, vcc
	v_cmp_gt_u32_e32 vcc, s85, v80
	v_add_u32_e32 v80, -8, v120
	s_nop 0
	v_cndmask_b32_e32 v35, v194, v35, vcc
	v_cmp_gt_u32_e32 vcc, s85, v80
	v_subrev_u32_e32 v80, 40, v120
	s_nop 0
	v_cndmask_b32_e32 v52, v194, v52, vcc
	v_cmp_gt_u32_e32 vcc, s85, v80
	v_add_u32_e32 v80, -9, v120
	s_nop 0
	v_cndmask_b32_e32 v36, v194, v36, vcc
	v_cmp_gt_u32_e32 vcc, s85, v80
	v_subrev_u32_e32 v80, 41, v120
	s_nop 0
	v_cndmask_b32_e32 v53, v194, v53, vcc
	v_cmp_gt_u32_e32 vcc, s85, v80
	v_add_u32_e32 v80, -10, v120
	s_nop 0
	v_cndmask_b32_e32 v37, v194, v37, vcc
	v_cmp_gt_u32_e32 vcc, s85, v80
	v_subrev_u32_e32 v80, 42, v120
	s_nop 0
	v_cndmask_b32_e32 v54, v194, v54, vcc
	v_cmp_gt_u32_e32 vcc, s85, v80
	v_add_u32_e32 v80, -11, v120
	s_nop 0
	v_cndmask_b32_e32 v38, v194, v38, vcc
	v_cmp_gt_u32_e32 vcc, s85, v80
	v_subrev_u32_e32 v80, 43, v120
	s_nop 0
	v_cndmask_b32_e32 v55, v194, v55, vcc
	v_cmp_gt_u32_e32 vcc, s85, v80
	v_add_u32_e32 v80, -16, v120
	s_nop 0
	v_cndmask_b32_e32 v39, v194, v39, vcc
	v_cmp_gt_u32_e32 vcc, s85, v80
	v_subrev_u32_e32 v80, 48, v120
	s_nop 0
	v_cndmask_b32_e32 v56, v194, v56, vcc
	v_cmp_gt_u32_e32 vcc, s85, v80
	v_subrev_u32_e32 v80, 17, v120
	s_nop 0
	v_cndmask_b32_e32 v40, v194, v40, vcc
	v_cmp_gt_u32_e32 vcc, s85, v80
	v_subrev_u32_e32 v80, 49, v120
	s_nop 0
	v_cndmask_b32_e32 v57, v194, v57, vcc
	v_cmp_gt_u32_e32 vcc, s85, v80
	v_subrev_u32_e32 v80, 18, v120
	s_nop 0
	v_cndmask_b32_e32 v41, v194, v41, vcc
	v_cmp_gt_u32_e32 vcc, s85, v80
	v_subrev_u32_e32 v80, 50, v120
	s_nop 0
	v_cndmask_b32_e32 v58, v194, v58, vcc
	v_cmp_gt_u32_e32 vcc, s85, v80
	v_subrev_u32_e32 v80, 19, v120
	s_nop 0
	v_cndmask_b32_e32 v42, v194, v42, vcc
	v_cmp_gt_u32_e32 vcc, s85, v80
	v_subrev_u32_e32 v80, 51, v120
	s_nop 0
	v_cndmask_b32_e32 v59, v194, v59, vcc
	v_cmp_gt_u32_e32 vcc, s85, v80
	v_subrev_u32_e32 v80, 24, v120
	s_nop 0
	v_cndmask_b32_e32 v43, v194, v43, vcc
	v_cmp_gt_u32_e32 vcc, s85, v80
	v_subrev_u32_e32 v80, 56, v120
	s_nop 0
	v_cndmask_b32_e32 v60, v194, v60, vcc
	v_cmp_gt_u32_e32 vcc, s85, v80
	v_subrev_u32_e32 v80, 25, v120
	s_nop 0
	v_cndmask_b32_e32 v44, v194, v44, vcc
	v_cmp_gt_u32_e32 vcc, s85, v80
	v_subrev_u32_e32 v80, 57, v120
	s_nop 0
	v_cndmask_b32_e32 v61, v194, v61, vcc
	v_cmp_gt_u32_e32 vcc, s85, v80
	v_subrev_u32_e32 v80, 26, v120
	s_nop 0
	v_cndmask_b32_e32 v45, v194, v45, vcc
	v_cmp_gt_u32_e32 vcc, s85, v80
	v_subrev_u32_e32 v80, 58, v120
	s_nop 0
	v_cndmask_b32_e32 v62, v194, v62, vcc
	v_cmp_gt_u32_e32 vcc, s85, v80
	v_subrev_u32_e32 v80, 27, v120
	s_nop 0
	v_cndmask_b32_e32 v46, v194, v46, vcc
	v_cmp_gt_u32_e32 vcc, s85, v80
	v_subrev_u32_e32 v80, 59, v120
	s_nop 0
	v_cndmask_b32_e32 v63, v194, v63, vcc
	v_cmp_gt_u32_e32 vcc, s85, v80
	s_nop 1
	v_cndmask_b32_e32 v47, v194, v47, vcc

; #define MFMA(a, b, c) __builtin_amdgcn_mfma_f32_32x32x16_bf16((a), (b), (c), 0, 0, 0)
; DI int crow(int r, int hi) { return (r & 3) + 8 * (r >> 2) + 4 * hi; }
; template <class MaskF>
; DI void attn_tile(const int tid, const char* ldsK, const char* ldsV, const bf16x8 (&qr)[4], f32x16 (&o)[2], float& m, float& l, const bool MASKED, MaskF mask) {
;   const int lane = tid & 63, l31 = lane & 31, hi = lane >> 5;
;   f32x16 p0, p1;
; #pragma unroll
;   for (int r = 0; r < 16; ++r) { p0[r] = 0.f; p1[r] = 0.f; }
;   const char* kp = ldsK + l31 * 144 + hi * 16;
; #pragma unroll
;   for (int s = 0; s < 4; ++s) {
;     const bf16x8 k0 = *(const bf16x8*)(kp + s * 32), k1 = *(const bf16x8*)(kp + 32 * 144 + s * 32);
;     p0 = MFMA(k0, qr[s], p0); p1 = MFMA(k1, qr[s], p1);
;   }
;   if (MASKED) {
; #pragma unroll
;     for (int r = 0; r < 16; ++r) {
;       const int kr = crow(r, hi);
;       p0[r] = mask(kr) ? p0[r] : NEGB; p1[r] = mask(kr + 32) ? p1[r] : NEGB;
;     }
; DI void nsa_item(const Params& p, int it, char* lds) {
;     ...
;   attn_stream(tid, proj, C_KSLC, C_VSLC, __builtin_popcount(anym),
;               [&](int ti, int row) { return b * S_ + jlist[ti] * 64 + row; },
;               [&](int ti) { const int jb = jlist[ti]; return (jb < cur) && ((allm >> jb) & 1u); },
;               [&](int ti, int kr) { const int jb = jlist[ti]; return ((mymask >> jb) & 1u) && (jb * 64 + kr <= t); },
;               qr, o, m, lsum, lds);
.LBB0_475:
	ds_read_b128 v[32:35], v219
	ds_read_b128 v[112:115], v219 offset:32
	ds_read_b128 v[124:127], v219 offset:4608
	ds_read_b128 v[116:119], v219 offset:96
	ds_read_b128 v[128:131], v219 offset:4640
	ds_read_b128 v[132:135], v219 offset:64
	ds_read_b128 v[136:139], v219 offset:4672
	ds_read_b128 v[140:143], v219 offset:4704
	v_mov_b32_e32 v120, s5
	s_waitcnt lgkmcnt(7)
	v_mfma_f32_32x32x16_bf16 v[48:63], v[32:35], v[64:67], 0
	s_waitcnt lgkmcnt(6)
	v_mfma_f32_32x32x16_bf16 v[48:63], v[112:115], v[68:71], v[48:63]
	s_waitcnt lgkmcnt(5)
	v_mfma_f32_32x32x16_bf16 v[32:47], v[124:127], v[64:67], 0
	s_waitcnt lgkmcnt(3)
	v_mfma_f32_32x32x16_bf16 v[32:47], v[128:131], v[68:71], v[32:47]
	s_waitcnt lgkmcnt(2)
	v_mfma_f32_32x32x16_bf16 v[48:63], v[132:135], v[72:75], v[48:63]
	s_waitcnt lgkmcnt(1)
	v_mfma_f32_32x32x16_bf16 v[32:47], v[136:139], v[72:75], v[32:47]
	ds_read_b32 v112, v120
	s_waitcnt lgkmcnt(0)
	v_lshlrev_b32_e64 v113, v112, 1
	v_and_b32_e32 v114, s2, v113
	v_mfma_f32_32x32x16_bf16 v[48:63], v[116:119], v[76:79], v[48:63]
	v_cmp_le_i32_e32 vcc, s36, v112
	v_cmp_eq_u32_e64 s[0:1], 0, v114
	s_or_b64 s[0:1], vcc, s[0:1]
	s_andn2_b64 vcc, exec, s[0:1]
	v_mfma_f32_32x32x16_bf16 v[32:47], v[140:143], v[76:79], v[32:47]
	s_cbranch_vccnz .LBB0_477
	v_and_b32_e32 v113, v113, v166
	v_lshlrev_b32_e32 v112, 6, v112
	v_cmp_ne_u32_e32 vcc, 0, v113
	v_or_b32_e32 v113, v112, v156
	v_cmp_le_i32_e64 s[0:1], v113, v147
	s_and_b64 s[0:1], vcc, s[0:1]
	v_or_b32_e32 v113, v112, v157
	v_cndmask_b32_e64 v48, v194, v48, s[0:1]
	v_cmp_le_i32_e64 s[0:1], v113, v147
	s_and_b64 s[0:1], vcc, s[0:1]
	v_or_b32_e32 v113, v112, v160
	v_cndmask_b32_e64 v32, v194, v32, s[0:1]
	v_cmp_le_i32_e64 s[0:1], v113, v147
	s_and_b64 s[0:1], vcc, s[0:1]
	v_or_b32_e32 v113, v112, v168
	v_cndmask_b32_e64 v49, v194, v49, s[0:1]
	v_cmp_le_i32_e64 s[0:1], v113, v147
	s_and_b64 s[0:1], vcc, s[0:1]
	v_or_b32_e32 v113, v112, v169
	v_cndmask_b32_e64 v33, v194, v33, s[0:1]
	v_cmp_le_i32_e64 s[0:1], v113, v147
	s_and_b64 s[0:1], vcc, s[0:1]
	v_or_b32_e32 v113, v112, v170
	v_cndmask_b32_e64 v50, v194, v50, s[0:1]
	v_cmp_le_i32_e64 s[0:1], v113, v147
	s_and_b64 s[0:1], vcc, s[0:1]
	v_or_b32_e32 v113, v112, v171
	v_cndmask_b32_e64 v34, v194, v34, s[0:1]
	v_cmp_le_i32_e64 s[0:1], v113, v147
	s_and_b64 s[0:1], vcc, s[0:1]
	v_or_b32_e32 v113, v112, v172
	v_cndmask_b32_e64 v51, v194, v51, s[0:1]
	v_cmp_le_i32_e64 s[0:1], v113, v147
	s_and_b64 s[0:1], vcc, s[0:1]
	v_or_b32_e32 v113, v112, v173
	v_cndmask_b32_e64 v35, v194, v35, s[0:1]
	v_cmp_le_i32_e64 s[0:1], v113, v147
	s_and_b64 s[0:1], vcc, s[0:1]
	v_or_b32_e32 v113, v112, v174
	v_cndmask_b32_e64 v52, v194, v52, s[0:1]
	v_cmp_le_i32_e64 s[0:1], v113, v147
	s_and_b64 s[0:1], vcc, s[0:1]
	v_or_b32_e32 v113, v112, v175
	v_cndmask_b32_e64 v36, v194, v36, s[0:1]
	v_cmp_le_i32_e64 s[0:1], v113, v147
	s_and_b64 s[0:1], vcc, s[0:1]
	v_or_b32_e32 v113, v112, v181
	v_cndmask_b32_e64 v53, v194, v53, s[0:1]
	v_cmp_le_i32_e64 s[0:1], v113, v147
	s_and_b64 s[0:1], vcc, s[0:1]
	v_or_b32_e32 v113, v112, v183
	v_cndmask_b32_e64 v37, v194, v37, s[0:1]
	v_cmp_le_i32_e64 s[0:1], v113, v147
	s_and_b64 s[0:1], vcc, s[0:1]
	v_or_b32_e32 v113, v112, v185
	v_cndmask_b32_e64 v54, v194, v54, s[0:1]
	v_cmp_le_i32_e64 s[0:1], v113, v147
	s_and_b64 s[0:1], vcc, s[0:1]
	v_or_b32_e32 v113, v112, v186
	v_cndmask_b32_e64 v38, v194, v38, s[0:1]
	v_cmp_le_i32_e64 s[0:1], v113, v147
	s_and_b64 s[0:1], vcc, s[0:1]
	v_or_b32_e32 v113, v112, v187
	v_cndmask_b32_e64 v55, v194, v55, s[0:1]
	v_cmp_le_i32_e64 s[0:1], v113, v147
	s_and_b64 s[0:1], vcc, s[0:1]
	v_or_b32_e32 v113, v112, v202
	v_cndmask_b32_e64 v39, v194, v39, s[0:1]
	v_cmp_le_i32_e64 s[0:1], v113, v147
	s_and_b64 s[0:1], vcc, s[0:1]
	v_or_b32_e32 v113, v112, v203
	v_cndmask_b32_e64 v56, v194, v56, s[0:1]
	v_cmp_le_i32_e64 s[0:1], v113, v147
	s_and_b64 s[0:1], vcc, s[0:1]
	v_or_b32_e32 v113, v112, v204
	v_cndmask_b32_e64 v40, v194, v40, s[0:1]
	v_cmp_le_i32_e64 s[0:1], v113, v147
	s_and_b64 s[0:1], vcc, s[0:1]
	v_or_b32_e32 v113, v112, v205
	v_cndmask_b32_e64 v57, v194, v57, s[0:1]
	v_cmp_le_i32_e64 s[0:1], v113, v147
	s_and_b64 s[0:1], vcc, s[0:1]
	v_or_b32_e32 v113, v112, v206
	v_cndmask_b32_e64 v41, v194, v41, s[0:1]
	v_cmp_le_i32_e64 s[0:1], v113, v147
	s_and_b64 s[0:1], vcc, s[0:1]
	v_or_b32_e32 v113, v112, v207
	v_cndmask_b32_e64 v58, v194, v58, s[0:1]
	v_cmp_le_i32_e64 s[0:1], v113, v147
	s_and_b64 s[0:1], vcc, s[0:1]
	v_or_b32_e32 v113, v112, v208
	v_cndmask_b32_e64 v42, v194, v42, s[0:1]
	v_cmp_le_i32_e64 s[0:1], v113, v147
	s_and_b64 s[0:1], vcc, s[0:1]
	v_or_b32_e32 v113, v112, v209
	v_cndmask_b32_e64 v59, v194, v59, s[0:1]
	v_cmp_le_i32_e64 s[0:1], v113, v147
	s_and_b64 s[0:1], vcc, s[0:1]
	v_or_b32_e32 v113, v112, v210
	v_cndmask_b32_e64 v43, v194, v43, s[0:1]
	v_cmp_le_i32_e64 s[0:1], v113, v147
	s_and_b64 s[0:1], vcc, s[0:1]
	v_or_b32_e32 v113, v112, v211
	v_cndmask_b32_e64 v60, v194, v60, s[0:1]
	v_cmp_le_i32_e64 s[0:1], v113, v147
	s_and_b64 s[0:1], vcc, s[0:1]
	v_or_b32_e32 v113, v112, v212
	v_cndmask_b32_e64 v44, v194, v44, s[0:1]
	v_cmp_le_i32_e64 s[0:1], v113, v147
	s_and_b64 s[0:1], vcc, s[0:1]
	v_or_b32_e32 v113, v112, v213
	v_cndmask_b32_e64 v61, v194, v61, s[0:1]
	v_cmp_le_i32_e64 s[0:1], v113, v147
	s_and_b64 s[0:1], vcc, s[0:1]
	v_or_b32_e32 v113, v112, v214
	v_cndmask_b32_e64 v45, v194, v45, s[0:1]
	v_cmp_le_i32_e64 s[0:1], v113, v147
	s_and_b64 s[0:1], vcc, s[0:1]
	v_or_b32_e32 v113, v112, v215
	v_cndmask_b32_e64 v62, v194, v62, s[0:1]
	v_cmp_le_i32_e64 s[0:1], v113, v147
	s_and_b64 s[0:1], vcc, s[0:1]
	v_or_b32_e32 v113, v112, v216
	v_cndmask_b32_e64 v46, v194, v46, s[0:1]
	v_cmp_le_i32_e64 s[0:1], v113, v147
	s_and_b64 s[0:1], vcc, s[0:1]
	v_or_b32_e32 v112, v112, v217
	v_cndmask_b32_e64 v63, v194, v63, s[0:1]
	v_cmp_le_i32_e64 s[0:1], v112, v147
	s_and_b64 vcc, vcc, s[0:1]
	v_cndmask_b32_e32 v47, v194, v47, vcc

; #define MFMA(a, b, c) __builtin_amdgcn_mfma_f32_32x32x16_bf16((a), (b), (c), 0, 0, 0)
; DI int crow(int r, int hi) { return (r & 3) + 8 * (r >> 2) + 4 * hi; }
; template <class MaskF>
; DI void attn_tile(const int tid, const char* ldsK, const char* ldsV, const bf16x8 (&qr)[4], f32x16 (&o)[2], float& m, float& l, const bool MASKED, MaskF mask) {
;   const int lane = tid & 63, l31 = lane & 31, hi = lane >> 5;
;   f32x16 p0, p1;
; #pragma unroll
;   for (int r = 0; r < 16; ++r) { p0[r] = 0.f; p1[r] = 0.f; }
;   const char* kp = ldsK + l31 * 144 + hi * 16;
; #pragma unroll
;   for (int s = 0; s < 4; ++s) {
;     const bf16x8 k0 = *(const bf16x8*)(kp + s * 32), k1 = *(const bf16x8*)(kp + 32 * 144 + s * 32);
;     p0 = MFMA(k0, qr[s], p0); p1 = MFMA(k1, qr[s], p1);
;   }
;   if (MASKED) {
; #pragma unroll
;     for (int r = 0; r < 16; ++r) {
;       const int kr = crow(r, hi);
;       p0[r] = mask(kr) ? p0[r] : NEGB; p1[r] = mask(kr + 32) ? p1[r] : NEGB;
;     }
; DI void nsa_item(const Params& p, int it, char* lds) {
;     ...
;   attn_stream(tid, proj, C_KSLC, C_VSLC, __builtin_popcount(anym),
;               [&](int ti, int row) { return b * S_ + jlist[ti] * 64 + row; },
;               [&](int ti) { const int jb = jlist[ti]; return (jb < cur) && ((allm >> jb) & 1u); },
;               [&](int ti, int kr) { const int jb = jlist[ti]; return ((mymask >> jb) & 1u) && (jb * 64 + kr <= t); },
;               qr, o, m, lsum, lds);
.LBB0_482:
	ds_read_b128 v[32:35], v219 offset:18432
	ds_read_b128 v[112:115], v219 offset:18464
	ds_read_b128 v[124:127], v219 offset:23040
	ds_read_b128 v[116:119], v219 offset:18528
	ds_read_b128 v[128:131], v219 offset:23072
	ds_read_b128 v[132:135], v219 offset:18496
	ds_read_b128 v[136:139], v219 offset:23104
	ds_read_b128 v[140:143], v219 offset:23136
	v_mov_b32_e32 v120, s5
	s_waitcnt lgkmcnt(7)
	v_mfma_f32_32x32x16_bf16 v[48:63], v[32:35], v[64:67], 0
	s_waitcnt lgkmcnt(6)
	v_mfma_f32_32x32x16_bf16 v[48:63], v[112:115], v[68:71], v[48:63]
	s_waitcnt lgkmcnt(5)
	v_mfma_f32_32x32x16_bf16 v[32:47], v[124:127], v[64:67], 0
	s_waitcnt lgkmcnt(3)
	v_mfma_f32_32x32x16_bf16 v[32:47], v[128:131], v[68:71], v[32:47]
	s_waitcnt lgkmcnt(2)
	v_mfma_f32_32x32x16_bf16 v[48:63], v[132:135], v[72:75], v[48:63]
	s_waitcnt lgkmcnt(1)
	v_mfma_f32_32x32x16_bf16 v[32:47], v[136:139], v[72:75], v[32:47]
	ds_read_b32 v112, v120 offset:4
	s_waitcnt lgkmcnt(0)
	v_lshlrev_b32_e64 v113, v112, 1
	v_and_b32_e32 v114, s2, v113
	v_mfma_f32_32x32x16_bf16 v[48:63], v[116:119], v[76:79], v[48:63]
	v_cmp_le_i32_e32 vcc, s36, v112
	v_cmp_eq_u32_e64 s[0:1], 0, v114
	s_or_b64 s[0:1], vcc, s[0:1]
	s_andn2_b64 vcc, exec, s[0:1]
	v_mfma_f32_32x32x16_bf16 v[32:47], v[140:143], v[76:79], v[32:47]
	s_cbranch_vccnz .LBB0_484
	v_and_b32_e32 v113, v113, v166
	v_lshlrev_b32_e32 v112, 6, v112
	v_cmp_ne_u32_e32 vcc, 0, v113
	v_or_b32_e32 v113, v112, v156
	v_cmp_le_i32_e64 s[0:1], v113, v147
	s_and_b64 s[0:1], vcc, s[0:1]
	v_or_b32_e32 v113, v112, v157
	v_cndmask_b32_e64 v48, v194, v48, s[0:1]
	v_cmp_le_i32_e64 s[0:1], v113, v147
	s_and_b64 s[0:1], vcc, s[0:1]
	v_or_b32_e32 v113, v112, v160
	v_cndmask_b32_e64 v32, v194, v32, s[0:1]
	v_cmp_le_i32_e64 s[0:1], v113, v147
	s_and_b64 s[0:1], vcc, s[0:1]
	v_or_b32_e32 v113, v112, v168
	v_cndmask_b32_e64 v49, v194, v49, s[0:1]
	v_cmp_le_i32_e64 s[0:1], v113, v147
	s_and_b64 s[0:1], vcc, s[0:1]
	v_or_b32_e32 v113, v112, v169
	v_cndmask_b32_e64 v33, v194, v33, s[0:1]
	v_cmp_le_i32_e64 s[0:1], v113, v147
	s_and_b64 s[0:1], vcc, s[0:1]
	v_or_b32_e32 v113, v112, v170
	v_cndmask_b32_e64 v50, v194, v50, s[0:1]
	v_cmp_le_i32_e64 s[0:1], v113, v147
	s_and_b64 s[0:1], vcc, s[0:1]
	v_or_b32_e32 v113, v112, v171
	v_cndmask_b32_e64 v34, v194, v34, s[0:1]
	v_cmp_le_i32_e64 s[0:1], v113, v147
	s_and_b64 s[0:1], vcc, s[0:1]
	v_or_b32_e32 v113, v112, v172
	v_cndmask_b32_e64 v51, v194, v51, s[0:1]
	v_cmp_le_i32_e64 s[0:1], v113, v147
	s_and_b64 s[0:1], vcc, s[0:1]
	v_or_b32_e32 v113, v112, v173
	v_cndmask_b32_e64 v35, v194, v35, s[0:1]
	v_cmp_le_i32_e64 s[0:1], v113, v147
	s_and_b64 s[0:1], vcc, s[0:1]
	v_or_b32_e32 v113, v112, v174
	v_cndmask_b32_e64 v52, v194, v52, s[0:1]
	v_cmp_le_i32_e64 s[0:1], v113, v147
	s_and_b64 s[0:1], vcc, s[0:1]
	v_or_b32_e32 v113, v112, v175
	v_cndmask_b32_e64 v36, v194, v36, s[0:1]
	v_cmp_le_i32_e64 s[0:1], v113, v147
	s_and_b64 s[0:1], vcc, s[0:1]
	v_or_b32_e32 v113, v112, v181
	v_cndmask_b32_e64 v53, v194, v53, s[0:1]
	v_cmp_le_i32_e64 s[0:1], v113, v147
	s_and_b64 s[0:1], vcc, s[0:1]
	v_or_b32_e32 v113, v112, v183
	v_cndmask_b32_e64 v37, v194, v37, s[0:1]
	v_cmp_le_i32_e64 s[0:1], v113, v147
	s_and_b64 s[0:1], vcc, s[0:1]
	v_or_b32_e32 v113, v112, v185
	v_cndmask_b32_e64 v54, v194, v54, s[0:1]
	v_cmp_le_i32_e64 s[0:1], v113, v147
	s_and_b64 s[0:1], vcc, s[0:1]
	v_or_b32_e32 v113, v112, v186
	v_cndmask_b32_e64 v38, v194, v38, s[0:1]
	v_cmp_le_i32_e64 s[0:1], v113, v147
	s_and_b64 s[0:1], vcc, s[0:1]
	v_or_b32_e32 v113, v112, v187
	v_cndmask_b32_e64 v55, v194, v55, s[0:1]
	v_cmp_le_i32_e64 s[0:1], v113, v147
	s_and_b64 s[0:1], vcc, s[0:1]
	v_or_b32_e32 v113, v112, v202
	v_cndmask_b32_e64 v39, v194, v39, s[0:1]
	v_cmp_le_i32_e64 s[0:1], v113, v147
	s_and_b64 s[0:1], vcc, s[0:1]
	v_or_b32_e32 v113, v112, v203
	v_cndmask_b32_e64 v56, v194, v56, s[0:1]
	v_cmp_le_i32_e64 s[0:1], v113, v147
	s_and_b64 s[0:1], vcc, s[0:1]
	v_or_b32_e32 v113, v112, v204
	v_cndmask_b32_e64 v40, v194, v40, s[0:1]
	v_cmp_le_i32_e64 s[0:1], v113, v147
	s_and_b64 s[0:1], vcc, s[0:1]
	v_or_b32_e32 v113, v112, v205
	v_cndmask_b32_e64 v57, v194, v57, s[0:1]
	v_cmp_le_i32_e64 s[0:1], v113, v147
	s_and_b64 s[0:1], vcc, s[0:1]
	v_or_b32_e32 v113, v112, v206
	v_cndmask_b32_e64 v41, v194, v41, s[0:1]
	v_cmp_le_i32_e64 s[0:1], v113, v147
	s_and_b64 s[0:1], vcc, s[0:1]
	v_or_b32_e32 v113, v112, v207
	v_cndmask_b32_e64 v58, v194, v58, s[0:1]
	v_cmp_le_i32_e64 s[0:1], v113, v147
	s_and_b64 s[0:1], vcc, s[0:1]
	v_or_b32_e32 v113, v112, v208
	v_cndmask_b32_e64 v42, v194, v42, s[0:1]
	v_cmp_le_i32_e64 s[0:1], v113, v147
	s_and_b64 s[0:1], vcc, s[0:1]
	v_or_b32_e32 v113, v112, v209
	v_cndmask_b32_e64 v59, v194, v59, s[0:1]
	v_cmp_le_i32_e64 s[0:1], v113, v147
	s_and_b64 s[0:1], vcc, s[0:1]
	v_or_b32_e32 v113, v112, v210
	v_cndmask_b32_e64 v43, v194, v43, s[0:1]
	v_cmp_le_i32_e64 s[0:1], v113, v147
	s_and_b64 s[0:1], vcc, s[0:1]
	v_or_b32_e32 v113, v112, v211
	v_cndmask_b32_e64 v60, v194, v60, s[0:1]
	v_cmp_le_i32_e64 s[0:1], v113, v147
	s_and_b64 s[0:1], vcc, s[0:1]
	v_or_b32_e32 v113, v112, v212
	v_cndmask_b32_e64 v44, v194, v44, s[0:1]
	v_cmp_le_i32_e64 s[0:1], v113, v147
	s_and_b64 s[0:1], vcc, s[0:1]
	v_or_b32_e32 v113, v112, v213
	v_cndmask_b32_e64 v61, v194, v61, s[0:1]
	v_cmp_le_i32_e64 s[0:1], v113, v147
	s_and_b64 s[0:1], vcc, s[0:1]
	v_or_b32_e32 v113, v112, v214
	v_cndmask_b32_e64 v45, v194, v45, s[0:1]
	v_cmp_le_i32_e64 s[0:1], v113, v147
	s_and_b64 s[0:1], vcc, s[0:1]
	v_or_b32_e32 v113, v112, v215
	v_cndmask_b32_e64 v62, v194, v62, s[0:1]
	v_cmp_le_i32_e64 s[0:1], v113, v147
	s_and_b64 s[0:1], vcc, s[0:1]
	v_or_b32_e32 v113, v112, v216
	v_cndmask_b32_e64 v46, v194, v46, s[0:1]
	v_cmp_le_i32_e64 s[0:1], v113, v147
	s_and_b64 s[0:1], vcc, s[0:1]
	v_or_b32_e32 v112, v112, v217
	v_cndmask_b32_e64 v63, v194, v63, s[0:1]
	v_cmp_le_i32_e64 s[0:1], v112, v147
	s_and_b64 vcc, vcc, s[0:1]
	v_cndmask_b32_e32 v47, v194, v47, vcc
